# fused residual epilogue's row-statistics exchange: L1-only invalidate after the arrival wait (the partial sums are read with agent-scope loads)
# speedup vs baseline: 1.0065x; 1.0065x over previous
;     __device__ __forceinline__ void fused(f32x4 (&acc)[2][2][4][2], const Unit& u, int wr, int wc, int fr, int fq, ldsp lds, int wid, int lane) const {
;     ...
;             __builtin_amdgcn_fence(__ATOMIC_ACQUIRE, "agent"); }
.LBB0_446:
	buffer_inv sc0
